# P1 K loop: last 4 of the 6 LDS-DMA pieces of phases 2 and 4 issued from inside the following MFMA cluster (counted wait 8 -> 4)
# speedup vs baseline: 1.0039x; 1.0031x over previous
.LBB0_130:
	s_ashr_i32 s13, s12, 31
	s_lshl_b64 s[14:15], s[12:13], 19
	v_readlane_b32 s16, v254, 39
	v_readlane_b32 s17, v254, 40
	s_add_u32 s14, s16, s14
	s_addc_u32 s15, s17, s15
	s_and_b64 s[16:17], s[0:1], exec
	s_cselect_b32 s13, s15, s19
	s_cselect_b32 s42, s14, s18
	s_ashr_i32 s11, s10, 31
	s_lshl_b64 s[16:17], s[10:11], 19
	s_add_u32 s16, s24, s16
	s_addc_u32 s17, s25, s17
	s_and_b64 s[22:23], s[0:1], exec
	s_cselect_b32 s11, s17, s21
	s_cselect_b32 s43, s16, s20
	s_add_u32 s18, s18, 0x40080
	s_addc_u32 s19, s19, 0
	s_add_u32 s44, s20, 0x100
	s_addc_u32 s45, s21, 0
	s_mov_b32 s46, -2
	ds_read_b128 v[152:155], v148
	ds_read_b128 v[156:159], v148 offset:1024
	ds_read_b128 v[160:163], v148 offset:2048
	ds_read_b128 v[164:167], v148 offset:3072
	ds_read_b128 v[168:171], v149
	ds_read_b128 v[172:175], v149 offset:1024
	ds_read_b128 v[176:179], v149 offset:2048
	ds_read_b128 v[180:183], v149 offset:3072
	s_add_u32 s20, s18, 0xfffc0080
	s_addc_u32 s21, s19, -1
	s_cmp_eq_u32 s46, 12
	s_cselect_b32 s23, s13, s21
	s_cselect_b32 s22, s42, s20
	s_cselect_b32 s21, s11, s45
	s_cselect_b32 s20, s43, s44
	s_add_i32 m0, s9, 0xc000
	ds_read_b128 v[184:187], v150
	ds_read_b128 v[188:191], v150 offset:1024
	ds_read_b128 v[192:195], v150 offset:2048
	ds_read_b128 v[196:199], v150 offset:3072
	ds_read_b128 v[200:203], v150 offset:4096
	ds_read_b128 v[204:207], v150 offset:5120
	ds_read_b128 v[208:211], v150 offset:6144
	ds_read_b128 v[212:215], v150 offset:7168
	global_load_lds_dwordx4 v136, s[18:19]
	s_add_i32 m0, s9, 0xe000
	s_nop 0
	global_load_lds_dwordx4 v138, s[18:19]
	s_waitcnt vmcnt(8)
	s_waitcnt lgkmcnt(0)
	s_barrier
	s_setprio 1
	s_waitcnt lgkmcnt(0)
	v_mfma_f32_16x16x32_bf16 v[124:127], v[152:155], v[184:187], 0
	v_mfma_f32_16x16x32_bf16 v[120:123], v[160:163], v[184:187], 0
	v_mfma_f32_16x16x32_bf16 v[116:119], v[152:155], v[192:195], 0
	v_mfma_f32_16x16x32_bf16 v[112:115], v[160:163], v[192:195], 0
	v_mfma_f32_16x16x32_bf16 v[100:103], v[152:155], v[200:203], 0
	v_mfma_f32_16x16x32_bf16 v[96:99], v[160:163], v[200:203], 0
	v_mfma_f32_16x16x32_bf16 v[84:87], v[152:155], v[208:211], 0
	v_mfma_f32_16x16x32_bf16 v[80:83], v[160:163], v[208:211], 0
	v_mfma_f32_16x16x32_bf16 v[124:127], v[156:159], v[188:191], v[124:127]
	v_mfma_f32_16x16x32_bf16 v[120:123], v[164:167], v[188:191], v[120:123]
	v_mfma_f32_16x16x32_bf16 v[116:119], v[156:159], v[196:199], v[116:119]
	v_mfma_f32_16x16x32_bf16 v[112:115], v[164:167], v[196:199], v[112:115]
	v_mfma_f32_16x16x32_bf16 v[100:103], v[156:159], v[204:207], v[100:103]
	v_mfma_f32_16x16x32_bf16 v[96:99], v[164:167], v[204:207], v[96:99]
	v_mfma_f32_16x16x32_bf16 v[84:87], v[156:159], v[212:215], v[84:87]
	v_mfma_f32_16x16x32_bf16 v[80:83], v[164:167], v[212:215], v[80:83]
	s_setprio 0
	s_setprio 1
	v_mfma_f32_16x16x32_bf16 v[108:111], v[168:171], v[184:187], 0
	v_mfma_f32_16x16x32_bf16 v[104:107], v[176:179], v[184:187], 0
	v_mfma_f32_16x16x32_bf16 v[92:95], v[168:171], v[192:195], 0
	v_mfma_f32_16x16x32_bf16 v[88:91], v[176:179], v[192:195], 0
	v_mfma_f32_16x16x32_bf16 v[76:79], v[168:171], v[200:203], 0
	v_mfma_f32_16x16x32_bf16 v[72:75], v[176:179], v[200:203], 0
	v_mfma_f32_16x16x32_bf16 v[68:71], v[168:171], v[208:211], 0
	v_mfma_f32_16x16x32_bf16 v[64:67], v[176:179], v[208:211], 0
	v_mfma_f32_16x16x32_bf16 v[108:111], v[172:175], v[188:191], v[108:111]
	v_mfma_f32_16x16x32_bf16 v[104:107], v[180:183], v[188:191], v[104:107]
	v_mfma_f32_16x16x32_bf16 v[92:95], v[172:175], v[196:199], v[92:95]
	v_mfma_f32_16x16x32_bf16 v[88:91], v[180:183], v[196:199], v[88:91]
	v_mfma_f32_16x16x32_bf16 v[76:79], v[172:175], v[204:207], v[76:79]
	v_mfma_f32_16x16x32_bf16 v[72:75], v[180:183], v[204:207], v[72:75]
	v_mfma_f32_16x16x32_bf16 v[68:71], v[172:175], v[212:215], v[68:71]
	v_mfma_f32_16x16x32_bf16 v[64:67], v[180:183], v[212:215], v[64:67]
	s_setprio 0
	s_barrier
	s_add_i32 s47, s38, s26
	s_mov_b32 m0, s47
	ds_read_b128 v[184:187], v150 offset:16384
	ds_read_b128 v[188:191], v150 offset:17408
	ds_read_b128 v[192:195], v150 offset:18432
	ds_read_b128 v[196:199], v150 offset:19456
	ds_read_b128 v[200:203], v150 offset:20480
	ds_read_b128 v[204:207], v150 offset:21504
	ds_read_b128 v[208:211], v150 offset:22528
	ds_read_b128 v[212:215], v150 offset:23552
	global_load_lds_dwordx4 v132, s[20:21]
	s_add_i32 m0, s47, 0x2000
	s_add_u32 s48, s20, 0x40000
	s_addc_u32 s49, s21, 0
	s_add_i32 s47, s39, s26
	global_load_lds_dwordx4 v128, s[20:21]


	s_add_u32 s84, s20, s4
	s_addc_u32 s85, s21, s5
	s_add_u32 s86, s22, s4
	s_addc_u32 s87, s23, s5
	s_waitcnt vmcnt(4)
	s_waitcnt lgkmcnt(0)
	s_barrier
	s_setprio 1
	s_waitcnt lgkmcnt(0)
	v_mfma_f32_16x16x32_bf16 v[60:63], v[152:155], v[184:187], 0
	v_mfma_f32_16x16x32_bf16 v[56:59], v[160:163], v[184:187], 0
	v_mfma_f32_16x16x32_bf16 v[52:55], v[152:155], v[192:195], 0
	v_mfma_f32_16x16x32_bf16 v[48:51], v[160:163], v[192:195], 0
	s_mov_b32 m0, s47
	v_mfma_f32_16x16x32_bf16 v[36:39], v[152:155], v[200:203], 0
	global_load_lds_dwordx4 v132, s[48:49]
	v_mfma_f32_16x16x32_bf16 v[32:35], v[160:163], v[200:203], 0
	v_mfma_f32_16x16x32_bf16 v[20:23], v[152:155], v[208:211], 0
	v_mfma_f32_16x16x32_bf16 v[16:19], v[160:163], v[208:211], 0
	v_mfma_f32_16x16x32_bf16 v[60:63], v[156:159], v[188:191], v[60:63]
	v_mfma_f32_16x16x32_bf16 v[56:59], v[164:167], v[188:191], v[56:59]
	v_mfma_f32_16x16x32_bf16 v[52:55], v[156:159], v[196:199], v[52:55]
	v_mfma_f32_16x16x32_bf16 v[48:51], v[164:167], v[196:199], v[48:51]
	s_add_i32 m0, s47, 0x2000
	v_mfma_f32_16x16x32_bf16 v[36:39], v[156:159], v[204:207], v[36:39]
	global_load_lds_dwordx4 v128, s[48:49]
	v_mfma_f32_16x16x32_bf16 v[32:35], v[164:167], v[204:207], v[32:35]
	v_mfma_f32_16x16x32_bf16 v[20:23], v[156:159], v[212:215], v[20:23]
	v_mfma_f32_16x16x32_bf16 v[16:19], v[164:167], v[212:215], v[16:19]
	s_setprio 0
	s_setprio 1
	v_mfma_f32_16x16x32_bf16 v[44:47], v[168:171], v[184:187], 0
	v_mfma_f32_16x16x32_bf16 v[40:43], v[176:179], v[184:187], 0
	v_mfma_f32_16x16x32_bf16 v[28:31], v[168:171], v[192:195], 0
	v_mfma_f32_16x16x32_bf16 v[24:27], v[176:179], v[192:195], 0
	s_mov_b32 m0, s9
	v_mfma_f32_16x16x32_bf16 v[12:15], v[168:171], v[200:203], 0
	global_load_lds_dwordx4 v134, s[22:23]
	v_mfma_f32_16x16x32_bf16 v[8:11], v[176:179], v[200:203], 0
	v_mfma_f32_16x16x32_bf16 v[4:7], v[168:171], v[208:211], 0
	v_mfma_f32_16x16x32_bf16 v[0:3], v[176:179], v[208:211], 0
	v_mfma_f32_16x16x32_bf16 v[44:47], v[172:175], v[188:191], v[44:47]
	v_mfma_f32_16x16x32_bf16 v[40:43], v[180:183], v[188:191], v[40:43]
	v_mfma_f32_16x16x32_bf16 v[28:31], v[172:175], v[196:199], v[28:31]
	v_mfma_f32_16x16x32_bf16 v[24:27], v[180:183], v[196:199], v[24:27]
	s_mov_b32 m0, s29
	v_mfma_f32_16x16x32_bf16 v[12:15], v[172:175], v[204:207], v[12:15]
	global_load_lds_dwordx4 v130, s[22:23]
	v_mfma_f32_16x16x32_bf16 v[8:11], v[180:183], v[204:207], v[8:11]
	v_mfma_f32_16x16x32_bf16 v[4:7], v[172:175], v[212:215], v[4:7]
	v_mfma_f32_16x16x32_bf16 v[0:3], v[180:183], v[212:215], v[0:3]
	s_setprio 0
	s_barrier
	s_add_i32 s47, 0, 0x18000
	v_add_u32_e32 v151, s47, v146
	s_add_i32 s48, 0, 0x1c000
	ds_read_b128 v[152:155], v151
	ds_read_b128 v[156:159], v151 offset:1024
	ds_read_b128 v[160:163], v151 offset:2048
	ds_read_b128 v[164:167], v151 offset:3072
	v_add_u32_e32 v151, s48, v146
	ds_read_b128 v[168:171], v151
	ds_read_b128 v[172:175], v151 offset:1024
	ds_read_b128 v[176:179], v151 offset:2048
	ds_read_b128 v[180:183], v151 offset:3072
	s_add_u32 s22, s22, 0x40000
	s_addc_u32 s23, s23, 0
	s_mov_b32 m0, s30
	ds_read_b128 v[184:187], v150 offset:32768
	ds_read_b128 v[188:191], v150 offset:33792
	ds_read_b128 v[192:195], v150 offset:34816
	ds_read_b128 v[196:199], v150 offset:35840
	ds_read_b128 v[200:203], v150 offset:36864
	ds_read_b128 v[204:207], v150 offset:37888
	ds_read_b128 v[208:211], v150 offset:38912
	ds_read_b128 v[212:215], v150 offset:39936
	global_load_lds_dwordx4 v134, s[22:23]
	s_mov_b32 m0, s31
	s_nop 0
	global_load_lds_dwordx4 v130, s[22:23]
	s_waitcnt vmcnt(8)
	s_waitcnt lgkmcnt(0)
	s_barrier
	s_setprio 1
	s_waitcnt lgkmcnt(0)
	v_mfma_f32_16x16x32_bf16 v[124:127], v[152:155], v[184:187], v[124:127]
	v_mfma_f32_16x16x32_bf16 v[120:123], v[160:163], v[184:187], v[120:123]
	v_mfma_f32_16x16x32_bf16 v[116:119], v[152:155], v[192:195], v[116:119]
	v_mfma_f32_16x16x32_bf16 v[112:115], v[160:163], v[192:195], v[112:115]
	v_mfma_f32_16x16x32_bf16 v[100:103], v[152:155], v[200:203], v[100:103]
	v_mfma_f32_16x16x32_bf16 v[96:99], v[160:163], v[200:203], v[96:99]
	v_mfma_f32_16x16x32_bf16 v[84:87], v[152:155], v[208:211], v[84:87]
	v_mfma_f32_16x16x32_bf16 v[80:83], v[160:163], v[208:211], v[80:83]
	v_mfma_f32_16x16x32_bf16 v[124:127], v[156:159], v[188:191], v[124:127]
	v_mfma_f32_16x16x32_bf16 v[120:123], v[164:167], v[188:191], v[120:123]
	v_mfma_f32_16x16x32_bf16 v[116:119], v[156:159], v[196:199], v[116:119]
	v_mfma_f32_16x16x32_bf16 v[112:115], v[164:167], v[196:199], v[112:115]
	v_mfma_f32_16x16x32_bf16 v[100:103], v[156:159], v[204:207], v[100:103]
	v_mfma_f32_16x16x32_bf16 v[96:99], v[164:167], v[204:207], v[96:99]
	v_mfma_f32_16x16x32_bf16 v[84:87], v[156:159], v[212:215], v[84:87]
	v_mfma_f32_16x16x32_bf16 v[80:83], v[164:167], v[212:215], v[80:83]
	s_setprio 0
	s_setprio 1
	v_mfma_f32_16x16x32_bf16 v[108:111], v[168:171], v[184:187], v[108:111]
	v_mfma_f32_16x16x32_bf16 v[104:107], v[176:179], v[184:187], v[104:107]
	v_mfma_f32_16x16x32_bf16 v[92:95], v[168:171], v[192:195], v[92:95]
	v_mfma_f32_16x16x32_bf16 v[88:91], v[176:179], v[192:195], v[88:91]
	v_mfma_f32_16x16x32_bf16 v[76:79], v[168:171], v[200:203], v[76:79]
	v_mfma_f32_16x16x32_bf16 v[72:75], v[176:179], v[200:203], v[72:75]
	v_mfma_f32_16x16x32_bf16 v[68:71], v[168:171], v[208:211], v[68:71]
	v_mfma_f32_16x16x32_bf16 v[64:67], v[176:179], v[208:211], v[64:67]
	v_mfma_f32_16x16x32_bf16 v[108:111], v[172:175], v[188:191], v[108:111]
	v_mfma_f32_16x16x32_bf16 v[104:107], v[180:183], v[188:191], v[104:107]
	v_mfma_f32_16x16x32_bf16 v[92:95], v[172:175], v[196:199], v[92:95]
	v_mfma_f32_16x16x32_bf16 v[88:91], v[180:183], v[196:199], v[88:91]
	v_mfma_f32_16x16x32_bf16 v[76:79], v[172:175], v[204:207], v[76:79]
	v_mfma_f32_16x16x32_bf16 v[72:75], v[180:183], v[204:207], v[72:75]
	v_mfma_f32_16x16x32_bf16 v[68:71], v[172:175], v[212:215], v[68:71]
	v_mfma_f32_16x16x32_bf16 v[64:67], v[180:183], v[212:215], v[64:67]
	s_setprio 0
	s_barrier
	s_add_i32 s22, s47, s26
	s_mov_b32 m0, s22
	ds_read_b128 v[184:187], v150 offset:49152
	ds_read_b128 v[188:191], v150 offset:50176
	ds_read_b128 v[192:195], v150 offset:51200
	ds_read_b128 v[196:199], v150 offset:52224
	ds_read_b128 v[200:203], v150 offset:53248
	ds_read_b128 v[204:207], v150 offset:54272
	ds_read_b128 v[208:211], v150 offset:55296
	ds_read_b128 v[212:215], v150 offset:56320
	global_load_lds_dwordx4 v132, s[84:85]
	s_add_i32 m0, s22, 0x2000
	s_add_u32 s20, s20, 0x40080
	s_addc_u32 s21, s21, 0
	s_add_i32 s22, s48, s26
	global_load_lds_dwordx4 v128, s[84:85]


	s_waitcnt vmcnt(4)
	s_waitcnt lgkmcnt(0)
	s_barrier
	s_setprio 1
	s_waitcnt lgkmcnt(0)
	v_mfma_f32_16x16x32_bf16 v[60:63], v[152:155], v[184:187], v[60:63]
	v_mfma_f32_16x16x32_bf16 v[56:59], v[160:163], v[184:187], v[56:59]
	v_mfma_f32_16x16x32_bf16 v[52:55], v[152:155], v[192:195], v[52:55]
	v_mfma_f32_16x16x32_bf16 v[48:51], v[160:163], v[192:195], v[48:51]
	s_mov_b32 m0, s22
	v_mfma_f32_16x16x32_bf16 v[36:39], v[152:155], v[200:203], v[36:39]
	global_load_lds_dwordx4 v132, s[20:21]
	v_mfma_f32_16x16x32_bf16 v[32:35], v[160:163], v[200:203], v[32:35]
	v_mfma_f32_16x16x32_bf16 v[20:23], v[152:155], v[208:211], v[20:23]
	v_mfma_f32_16x16x32_bf16 v[16:19], v[160:163], v[208:211], v[16:19]
	v_mfma_f32_16x16x32_bf16 v[60:63], v[156:159], v[188:191], v[60:63]
	v_mfma_f32_16x16x32_bf16 v[56:59], v[164:167], v[188:191], v[56:59]
	v_mfma_f32_16x16x32_bf16 v[52:55], v[156:159], v[196:199], v[52:55]
	v_mfma_f32_16x16x32_bf16 v[48:51], v[164:167], v[196:199], v[48:51]
	s_add_i32 m0, s22, 0x2000
	v_mfma_f32_16x16x32_bf16 v[36:39], v[156:159], v[204:207], v[36:39]
	global_load_lds_dwordx4 v128, s[20:21]
	v_mfma_f32_16x16x32_bf16 v[32:35], v[164:167], v[204:207], v[32:35]
	v_mfma_f32_16x16x32_bf16 v[20:23], v[156:159], v[212:215], v[20:23]
	v_mfma_f32_16x16x32_bf16 v[16:19], v[164:167], v[212:215], v[16:19]
	s_setprio 0
	s_setprio 1
	v_mfma_f32_16x16x32_bf16 v[44:47], v[168:171], v[184:187], v[44:47]
	v_mfma_f32_16x16x32_bf16 v[40:43], v[176:179], v[184:187], v[40:43]
	v_mfma_f32_16x16x32_bf16 v[28:31], v[168:171], v[192:195], v[28:31]
	v_mfma_f32_16x16x32_bf16 v[24:27], v[176:179], v[192:195], v[24:27]
	s_mov_b32 m0, s34
	v_mfma_f32_16x16x32_bf16 v[12:15], v[168:171], v[200:203], v[12:15]
	global_load_lds_dwordx4 v134, s[86:87]
	v_mfma_f32_16x16x32_bf16 v[8:11], v[176:179], v[200:203], v[8:11]
	v_mfma_f32_16x16x32_bf16 v[4:7], v[168:171], v[208:211], v[4:7]
	v_mfma_f32_16x16x32_bf16 v[0:3], v[176:179], v[208:211], v[0:3]
	v_mfma_f32_16x16x32_bf16 v[44:47], v[172:175], v[188:191], v[44:47]
	v_mfma_f32_16x16x32_bf16 v[40:43], v[180:183], v[188:191], v[40:43]
	v_mfma_f32_16x16x32_bf16 v[28:31], v[172:175], v[196:199], v[28:31]
	v_mfma_f32_16x16x32_bf16 v[24:27], v[180:183], v[196:199], v[24:27]
	s_mov_b32 m0, s35
	v_mfma_f32_16x16x32_bf16 v[12:15], v[172:175], v[204:207], v[12:15]
	global_load_lds_dwordx4 v130, s[86:87]
	v_mfma_f32_16x16x32_bf16 v[8:11], v[180:183], v[204:207], v[8:11]
	v_mfma_f32_16x16x32_bf16 v[4:7], v[172:175], v[212:215], v[4:7]
	v_mfma_f32_16x16x32_bf16 v[0:3], v[180:183], v[212:215], v[0:3]
	s_setprio 0
	s_barrier
	s_add_i32 s46, s46, 2
	s_add_u32 s18, s18, 0x100
	s_addc_u32 s19, s19, 0
	s_add_u32 s44, s44, 0x100
	s_addc_u32 s45, s45, 0
.LBB0_131:
	ds_read_b128 v[152:155], v148
	ds_read_b128 v[156:159], v148 offset:1024
	ds_read_b128 v[160:163], v148 offset:2048
	ds_read_b128 v[164:167], v148 offset:3072
	ds_read_b128 v[168:171], v149
	ds_read_b128 v[172:175], v149 offset:1024
	ds_read_b128 v[176:179], v149 offset:2048
	ds_read_b128 v[180:183], v149 offset:3072
	s_add_u32 s20, s18, 0xfffc0080
	s_addc_u32 s21, s19, -1
	s_cmp_eq_u32 s46, 12
	s_cselect_b32 s23, s13, s21
	s_cselect_b32 s22, s42, s20
	s_cselect_b32 s21, s11, s45
	s_cselect_b32 s20, s43, s44
	s_add_i32 m0, s9, 0xc000
	ds_read_b128 v[184:187], v150
	ds_read_b128 v[188:191], v150 offset:1024
	ds_read_b128 v[192:195], v150 offset:2048
	ds_read_b128 v[196:199], v150 offset:3072
	ds_read_b128 v[200:203], v150 offset:4096
	ds_read_b128 v[204:207], v150 offset:5120
	ds_read_b128 v[208:211], v150 offset:6144
	ds_read_b128 v[212:215], v150 offset:7168
	global_load_lds_dwordx4 v136, s[18:19]
	s_add_i32 m0, s9, 0xe000
	s_nop 0
	global_load_lds_dwordx4 v138, s[18:19]
	s_waitcnt vmcnt(8)
	s_waitcnt lgkmcnt(0)
	s_barrier
	s_setprio 1
	s_waitcnt lgkmcnt(0)
	v_mfma_f32_16x16x32_bf16 v[124:127], v[152:155], v[184:187], v[124:127]
	v_mfma_f32_16x16x32_bf16 v[120:123], v[160:163], v[184:187], v[120:123]
	v_mfma_f32_16x16x32_bf16 v[116:119], v[152:155], v[192:195], v[116:119]
	v_mfma_f32_16x16x32_bf16 v[112:115], v[160:163], v[192:195], v[112:115]
	v_mfma_f32_16x16x32_bf16 v[100:103], v[152:155], v[200:203], v[100:103]
	v_mfma_f32_16x16x32_bf16 v[96:99], v[160:163], v[200:203], v[96:99]
	v_mfma_f32_16x16x32_bf16 v[84:87], v[152:155], v[208:211], v[84:87]
	v_mfma_f32_16x16x32_bf16 v[80:83], v[160:163], v[208:211], v[80:83]
	v_mfma_f32_16x16x32_bf16 v[124:127], v[156:159], v[188:191], v[124:127]
	v_mfma_f32_16x16x32_bf16 v[120:123], v[164:167], v[188:191], v[120:123]
	v_mfma_f32_16x16x32_bf16 v[116:119], v[156:159], v[196:199], v[116:119]
	v_mfma_f32_16x16x32_bf16 v[112:115], v[164:167], v[196:199], v[112:115]
	v_mfma_f32_16x16x32_bf16 v[100:103], v[156:159], v[204:207], v[100:103]
	v_mfma_f32_16x16x32_bf16 v[96:99], v[164:167], v[204:207], v[96:99]
	v_mfma_f32_16x16x32_bf16 v[84:87], v[156:159], v[212:215], v[84:87]
	v_mfma_f32_16x16x32_bf16 v[80:83], v[164:167], v[212:215], v[80:83]
	s_setprio 0
	s_setprio 1
	v_mfma_f32_16x16x32_bf16 v[108:111], v[168:171], v[184:187], v[108:111]
	v_mfma_f32_16x16x32_bf16 v[104:107], v[176:179], v[184:187], v[104:107]
	v_mfma_f32_16x16x32_bf16 v[92:95], v[168:171], v[192:195], v[92:95]
	v_mfma_f32_16x16x32_bf16 v[88:91], v[176:179], v[192:195], v[88:91]
	v_mfma_f32_16x16x32_bf16 v[76:79], v[168:171], v[200:203], v[76:79]
	v_mfma_f32_16x16x32_bf16 v[72:75], v[176:179], v[200:203], v[72:75]
	v_mfma_f32_16x16x32_bf16 v[68:71], v[168:171], v[208:211], v[68:71]
	v_mfma_f32_16x16x32_bf16 v[64:67], v[176:179], v[208:211], v[64:67]
	v_mfma_f32_16x16x32_bf16 v[108:111], v[172:175], v[188:191], v[108:111]
	v_mfma_f32_16x16x32_bf16 v[104:107], v[180:183], v[188:191], v[104:107]
	v_mfma_f32_16x16x32_bf16 v[92:95], v[172:175], v[196:199], v[92:95]
	v_mfma_f32_16x16x32_bf16 v[88:91], v[180:183], v[196:199], v[88:91]
	v_mfma_f32_16x16x32_bf16 v[76:79], v[172:175], v[204:207], v[76:79]
	v_mfma_f32_16x16x32_bf16 v[72:75], v[180:183], v[204:207], v[72:75]
	v_mfma_f32_16x16x32_bf16 v[68:71], v[172:175], v[212:215], v[68:71]
	v_mfma_f32_16x16x32_bf16 v[64:67], v[180:183], v[212:215], v[64:67]
	s_setprio 0
	s_barrier
	s_add_i32 s47, s38, s26
	s_mov_b32 m0, s47
	ds_read_b128 v[184:187], v150 offset:16384
	ds_read_b128 v[188:191], v150 offset:17408
	ds_read_b128 v[192:195], v150 offset:18432
	ds_read_b128 v[196:199], v150 offset:19456
	ds_read_b128 v[200:203], v150 offset:20480
	ds_read_b128 v[204:207], v150 offset:21504
	ds_read_b128 v[208:211], v150 offset:22528
	ds_read_b128 v[212:215], v150 offset:23552
	global_load_lds_dwordx4 v132, s[20:21]
	s_add_i32 m0, s47, 0x2000
	s_add_u32 s48, s20, 0x40000
	s_addc_u32 s49, s21, 0
	s_add_i32 s47, s39, s26
	global_load_lds_dwordx4 v128, s[20:21]


	s_add_u32 s84, s20, s4
	s_addc_u32 s85, s21, s5
	s_add_u32 s86, s22, s4
	s_addc_u32 s87, s23, s5
	s_waitcnt vmcnt(4)
	s_waitcnt lgkmcnt(0)
	s_barrier
	s_setprio 1
	s_waitcnt lgkmcnt(0)
	v_mfma_f32_16x16x32_bf16 v[60:63], v[152:155], v[184:187], v[60:63]
	v_mfma_f32_16x16x32_bf16 v[56:59], v[160:163], v[184:187], v[56:59]
	v_mfma_f32_16x16x32_bf16 v[52:55], v[152:155], v[192:195], v[52:55]
	v_mfma_f32_16x16x32_bf16 v[48:51], v[160:163], v[192:195], v[48:51]
	s_mov_b32 m0, s47
	v_mfma_f32_16x16x32_bf16 v[36:39], v[152:155], v[200:203], v[36:39]
	global_load_lds_dwordx4 v132, s[48:49]
	v_mfma_f32_16x16x32_bf16 v[32:35], v[160:163], v[200:203], v[32:35]
	v_mfma_f32_16x16x32_bf16 v[20:23], v[152:155], v[208:211], v[20:23]
	v_mfma_f32_16x16x32_bf16 v[16:19], v[160:163], v[208:211], v[16:19]
	v_mfma_f32_16x16x32_bf16 v[60:63], v[156:159], v[188:191], v[60:63]
	v_mfma_f32_16x16x32_bf16 v[56:59], v[164:167], v[188:191], v[56:59]
	v_mfma_f32_16x16x32_bf16 v[52:55], v[156:159], v[196:199], v[52:55]
	v_mfma_f32_16x16x32_bf16 v[48:51], v[164:167], v[196:199], v[48:51]
	s_add_i32 m0, s47, 0x2000
	v_mfma_f32_16x16x32_bf16 v[36:39], v[156:159], v[204:207], v[36:39]
	global_load_lds_dwordx4 v128, s[48:49]
	v_mfma_f32_16x16x32_bf16 v[32:35], v[164:167], v[204:207], v[32:35]
	v_mfma_f32_16x16x32_bf16 v[20:23], v[156:159], v[212:215], v[20:23]
	v_mfma_f32_16x16x32_bf16 v[16:19], v[164:167], v[212:215], v[16:19]
	s_setprio 0
	s_setprio 1
	v_mfma_f32_16x16x32_bf16 v[44:47], v[168:171], v[184:187], v[44:47]
	v_mfma_f32_16x16x32_bf16 v[40:43], v[176:179], v[184:187], v[40:43]
	v_mfma_f32_16x16x32_bf16 v[28:31], v[168:171], v[192:195], v[28:31]
	v_mfma_f32_16x16x32_bf16 v[24:27], v[176:179], v[192:195], v[24:27]
	s_mov_b32 m0, s9
	v_mfma_f32_16x16x32_bf16 v[12:15], v[168:171], v[200:203], v[12:15]
	global_load_lds_dwordx4 v134, s[22:23]
	v_mfma_f32_16x16x32_bf16 v[8:11], v[176:179], v[200:203], v[8:11]
	v_mfma_f32_16x16x32_bf16 v[4:7], v[168:171], v[208:211], v[4:7]
	v_mfma_f32_16x16x32_bf16 v[0:3], v[176:179], v[208:211], v[0:3]
	v_mfma_f32_16x16x32_bf16 v[44:47], v[172:175], v[188:191], v[44:47]
	v_mfma_f32_16x16x32_bf16 v[40:43], v[180:183], v[188:191], v[40:43]
	v_mfma_f32_16x16x32_bf16 v[28:31], v[172:175], v[196:199], v[28:31]
	v_mfma_f32_16x16x32_bf16 v[24:27], v[180:183], v[196:199], v[24:27]
	s_mov_b32 m0, s29
	v_mfma_f32_16x16x32_bf16 v[12:15], v[172:175], v[204:207], v[12:15]
	global_load_lds_dwordx4 v130, s[22:23]
	v_mfma_f32_16x16x32_bf16 v[8:11], v[180:183], v[204:207], v[8:11]
	v_mfma_f32_16x16x32_bf16 v[4:7], v[172:175], v[212:215], v[4:7]
	v_mfma_f32_16x16x32_bf16 v[0:3], v[180:183], v[212:215], v[0:3]
	s_setprio 0
	s_barrier
	s_add_i32 s47, 0, 0x18000
	v_add_u32_e32 v151, s47, v146
	s_add_i32 s48, 0, 0x1c000
	ds_read_b128 v[152:155], v151
	ds_read_b128 v[156:159], v151 offset:1024
	ds_read_b128 v[160:163], v151 offset:2048
	ds_read_b128 v[164:167], v151 offset:3072
	v_add_u32_e32 v151, s48, v146
	ds_read_b128 v[168:171], v151
	ds_read_b128 v[172:175], v151 offset:1024
	ds_read_b128 v[176:179], v151 offset:2048
	ds_read_b128 v[180:183], v151 offset:3072
	s_add_u32 s22, s22, 0x40000
	s_addc_u32 s23, s23, 0
	s_mov_b32 m0, s30
	ds_read_b128 v[184:187], v150 offset:32768
	ds_read_b128 v[188:191], v150 offset:33792
	ds_read_b128 v[192:195], v150 offset:34816
	ds_read_b128 v[196:199], v150 offset:35840
	ds_read_b128 v[200:203], v150 offset:36864
	ds_read_b128 v[204:207], v150 offset:37888
	ds_read_b128 v[208:211], v150 offset:38912
	ds_read_b128 v[212:215], v150 offset:39936
	global_load_lds_dwordx4 v134, s[22:23]
	s_mov_b32 m0, s31
	s_nop 0
	global_load_lds_dwordx4 v130, s[22:23]
	s_waitcnt vmcnt(8)
	s_waitcnt lgkmcnt(0)
	s_barrier
	s_setprio 1
	s_waitcnt lgkmcnt(0)
	v_mfma_f32_16x16x32_bf16 v[124:127], v[152:155], v[184:187], v[124:127]
	v_mfma_f32_16x16x32_bf16 v[120:123], v[160:163], v[184:187], v[120:123]
	v_mfma_f32_16x16x32_bf16 v[116:119], v[152:155], v[192:195], v[116:119]
	v_mfma_f32_16x16x32_bf16 v[112:115], v[160:163], v[192:195], v[112:115]
	v_mfma_f32_16x16x32_bf16 v[100:103], v[152:155], v[200:203], v[100:103]
	v_mfma_f32_16x16x32_bf16 v[96:99], v[160:163], v[200:203], v[96:99]
	v_mfma_f32_16x16x32_bf16 v[84:87], v[152:155], v[208:211], v[84:87]
	v_mfma_f32_16x16x32_bf16 v[80:83], v[160:163], v[208:211], v[80:83]
	v_mfma_f32_16x16x32_bf16 v[124:127], v[156:159], v[188:191], v[124:127]
	v_mfma_f32_16x16x32_bf16 v[120:123], v[164:167], v[188:191], v[120:123]
	v_mfma_f32_16x16x32_bf16 v[116:119], v[156:159], v[196:199], v[116:119]
	v_mfma_f32_16x16x32_bf16 v[112:115], v[164:167], v[196:199], v[112:115]
	v_mfma_f32_16x16x32_bf16 v[100:103], v[156:159], v[204:207], v[100:103]
	v_mfma_f32_16x16x32_bf16 v[96:99], v[164:167], v[204:207], v[96:99]
	v_mfma_f32_16x16x32_bf16 v[84:87], v[156:159], v[212:215], v[84:87]
	v_mfma_f32_16x16x32_bf16 v[80:83], v[164:167], v[212:215], v[80:83]
	s_setprio 0
	s_setprio 1
	v_mfma_f32_16x16x32_bf16 v[108:111], v[168:171], v[184:187], v[108:111]
	v_mfma_f32_16x16x32_bf16 v[104:107], v[176:179], v[184:187], v[104:107]
	v_mfma_f32_16x16x32_bf16 v[92:95], v[168:171], v[192:195], v[92:95]
	v_mfma_f32_16x16x32_bf16 v[88:91], v[176:179], v[192:195], v[88:91]
	v_mfma_f32_16x16x32_bf16 v[76:79], v[168:171], v[200:203], v[76:79]
	v_mfma_f32_16x16x32_bf16 v[72:75], v[176:179], v[200:203], v[72:75]
	v_mfma_f32_16x16x32_bf16 v[68:71], v[168:171], v[208:211], v[68:71]
	v_mfma_f32_16x16x32_bf16 v[64:67], v[176:179], v[208:211], v[64:67]
	v_mfma_f32_16x16x32_bf16 v[108:111], v[172:175], v[188:191], v[108:111]
	v_mfma_f32_16x16x32_bf16 v[104:107], v[180:183], v[188:191], v[104:107]
	v_mfma_f32_16x16x32_bf16 v[92:95], v[172:175], v[196:199], v[92:95]
	v_mfma_f32_16x16x32_bf16 v[88:91], v[180:183], v[196:199], v[88:91]
	v_mfma_f32_16x16x32_bf16 v[76:79], v[172:175], v[204:207], v[76:79]
	v_mfma_f32_16x16x32_bf16 v[72:75], v[180:183], v[204:207], v[72:75]
	v_mfma_f32_16x16x32_bf16 v[68:71], v[172:175], v[212:215], v[68:71]
	v_mfma_f32_16x16x32_bf16 v[64:67], v[180:183], v[212:215], v[64:67]
	s_setprio 0
	s_barrier
	s_add_i32 s22, s47, s26
	s_mov_b32 m0, s22
	ds_read_b128 v[184:187], v150 offset:49152
	ds_read_b128 v[188:191], v150 offset:50176
	ds_read_b128 v[192:195], v150 offset:51200
	ds_read_b128 v[196:199], v150 offset:52224
	ds_read_b128 v[200:203], v150 offset:53248
	ds_read_b128 v[204:207], v150 offset:54272
	ds_read_b128 v[208:211], v150 offset:55296
	ds_read_b128 v[212:215], v150 offset:56320
	global_load_lds_dwordx4 v132, s[84:85]
	s_add_i32 m0, s22, 0x2000
	s_add_u32 s20, s20, 0x40080
	s_addc_u32 s21, s21, 0
	s_add_i32 s22, s48, s26
	global_load_lds_dwordx4 v128, s[84:85]


	s_waitcnt vmcnt(4)
	s_waitcnt lgkmcnt(0)
	s_barrier
	s_setprio 1
	s_waitcnt lgkmcnt(0)
	v_mfma_f32_16x16x32_bf16 v[60:63], v[152:155], v[184:187], v[60:63]
	v_mfma_f32_16x16x32_bf16 v[56:59], v[160:163], v[184:187], v[56:59]
	v_mfma_f32_16x16x32_bf16 v[52:55], v[152:155], v[192:195], v[52:55]
	v_mfma_f32_16x16x32_bf16 v[48:51], v[160:163], v[192:195], v[48:51]
	s_mov_b32 m0, s22
	v_mfma_f32_16x16x32_bf16 v[36:39], v[152:155], v[200:203], v[36:39]
	global_load_lds_dwordx4 v132, s[20:21]
	v_mfma_f32_16x16x32_bf16 v[32:35], v[160:163], v[200:203], v[32:35]
	v_mfma_f32_16x16x32_bf16 v[20:23], v[152:155], v[208:211], v[20:23]
	v_mfma_f32_16x16x32_bf16 v[16:19], v[160:163], v[208:211], v[16:19]
	v_mfma_f32_16x16x32_bf16 v[60:63], v[156:159], v[188:191], v[60:63]
	v_mfma_f32_16x16x32_bf16 v[56:59], v[164:167], v[188:191], v[56:59]
	v_mfma_f32_16x16x32_bf16 v[52:55], v[156:159], v[196:199], v[52:55]
	v_mfma_f32_16x16x32_bf16 v[48:51], v[164:167], v[196:199], v[48:51]
	s_add_i32 m0, s22, 0x2000
	v_mfma_f32_16x16x32_bf16 v[36:39], v[156:159], v[204:207], v[36:39]
	global_load_lds_dwordx4 v128, s[20:21]
	v_mfma_f32_16x16x32_bf16 v[32:35], v[164:167], v[204:207], v[32:35]
	v_mfma_f32_16x16x32_bf16 v[20:23], v[156:159], v[212:215], v[20:23]
	v_mfma_f32_16x16x32_bf16 v[16:19], v[164:167], v[212:215], v[16:19]
	s_setprio 0
	s_setprio 1
	v_mfma_f32_16x16x32_bf16 v[44:47], v[168:171], v[184:187], v[44:47]
	v_mfma_f32_16x16x32_bf16 v[40:43], v[176:179], v[184:187], v[40:43]
	v_mfma_f32_16x16x32_bf16 v[28:31], v[168:171], v[192:195], v[28:31]
	v_mfma_f32_16x16x32_bf16 v[24:27], v[176:179], v[192:195], v[24:27]
	s_mov_b32 m0, s34
	v_mfma_f32_16x16x32_bf16 v[12:15], v[168:171], v[200:203], v[12:15]
	global_load_lds_dwordx4 v134, s[86:87]
	v_mfma_f32_16x16x32_bf16 v[8:11], v[176:179], v[200:203], v[8:11]
	v_mfma_f32_16x16x32_bf16 v[4:7], v[168:171], v[208:211], v[4:7]
	v_mfma_f32_16x16x32_bf16 v[0:3], v[176:179], v[208:211], v[0:3]
	v_mfma_f32_16x16x32_bf16 v[44:47], v[172:175], v[188:191], v[44:47]
	v_mfma_f32_16x16x32_bf16 v[40:43], v[180:183], v[188:191], v[40:43]
	v_mfma_f32_16x16x32_bf16 v[28:31], v[172:175], v[196:199], v[28:31]
	v_mfma_f32_16x16x32_bf16 v[24:27], v[180:183], v[196:199], v[24:27]
	s_mov_b32 m0, s35
	v_mfma_f32_16x16x32_bf16 v[12:15], v[172:175], v[204:207], v[12:15]
	global_load_lds_dwordx4 v130, s[86:87]
	v_mfma_f32_16x16x32_bf16 v[8:11], v[180:183], v[204:207], v[8:11]
	v_mfma_f32_16x16x32_bf16 v[4:7], v[172:175], v[212:215], v[4:7]
	v_mfma_f32_16x16x32_bf16 v[0:3], v[180:183], v[212:215], v[0:3]
	s_setprio 0
	s_barrier
	s_add_i32 s46, s46, 2
	s_add_u32 s18, s18, 0x100
	s_addc_u32 s19, s19, 0
	s_add_u32 s44, s44, 0x100
	s_addc_u32 s45, s45, 0
	s_cmp_gt_u32 s46, 13
	s_cbranch_scc0 .LBB0_131
	s_and_b64 vcc, exec, s[6:7]
	s_cbranch_vccz .LBB0_134
	s_barrier
